# grid barrier released by polling the global arrival counter (no generation-word bump hop), on top of the combined version
# baseline (speedup 1.0000x reference)
.LBB0_1181:
	s_or_b64 exec, exec, s[2:3]
	v_cvt_f32_u32_e32 v5, v3
	s_waitcnt vmcnt(0)
	v_readfirstlane_b32 s2, v4
	v_sub_u32_e32 v4, 0, v3
	v_rcp_iflag_f32_e32 v5, v5
	v_add_u32_e32 v6, s2, v0
	v_mul_f32_e32 v5, 0x4f7ffffe, v5
	v_cvt_u32_f32_e32 v5, v5
	v_mul_lo_u32 v0, v4, v5
	v_mul_hi_u32 v0, v5, v0
	v_add_u32_e32 v0, v5, v0
	v_mul_hi_u32 v0, v6, v0
	v_mul_lo_u32 v4, v0, v3
	v_sub_u32_e32 v4, v6, v4
	v_add_u32_e32 v5, 1, v0
	v_cmp_ge_u32_e32 vcc, v4, v3
	s_nop 1
	v_cndmask_b32_e32 v0, v0, v5, vcc
	v_sub_u32_e32 v5, v4, v3
	v_cndmask_b32_e32 v4, v4, v5, vcc
	v_add_u32_e32 v5, 1, v0
	v_cmp_ge_u32_e32 vcc, v4, v3
	v_add_u32_e32 v4, 1, v6
	s_nop 0
	v_cndmask_b32_e32 v0, v0, v5, vcc
	v_mul_lo_u32 v5, v3, v0
	v_add_u32_e32 v3, v5, v3
	v_cmp_ne_u32_e32 vcc, v4, v3
	s_and_saveexec_b64 s[2:3], vcc
	s_xor_b64 s[2:3], exec, s[2:3]
	s_cbranch_execz .LBB0_1195
	v_readlane_b32 s4, v252, 11
	v_readlane_b32 s5, v252, 12
	s_waitcnt lgkmcnt(0)
	v_add_u32_e32 v6, 1, v0
	v_mul_lo_u32 v6, v6, v2
	s_nop 3
	global_load_dword v2, v1, s[4:5] sc1
	s_waitcnt vmcnt(0)
	v_cmp_gt_u32_e32 vcc, v6, v2
	s_and_saveexec_b64 s[4:5], vcc
	s_cbranch_execz .LBB0_1194
	s_mov_b32 s16, 1
	s_mov_b64 s[6:7], 0
	s_branch .LBB0_1185

.LBB0_1187:
	v_readlane_b32 s10, v252, 11
	v_readlane_b32 s11, v252, 12
	s_add_i32 s16, s16, 1
	s_mov_b64 s[12:13], -1
	s_nop 2
	global_load_dword v2, v1, s[10:11] sc1
	s_waitcnt vmcnt(0)
	v_cmp_le_u32_e32 vcc, v6, v2
	s_orn2_b64 s[10:11], vcc, exec
	s_branch .LBB0_1184

.LBB0_1198:
	s_or_b64 exec, exec, s[4:5]
	s_waitcnt vmcnt(0)
	v_readfirstlane_b32 s2, v3
	v_sub_u32_e32 v4, 0, v2
	s_mov_b64 s[4:5], -1
	v_add_u32_e32 v3, s2, v0
	v_cvt_f32_u32_e32 v0, v2
	v_readlane_b32 s2, v252, 13
	v_readlane_b32 s3, v252, 14
	v_rcp_iflag_f32_e32 v0, v0
	s_nop 0
	v_mul_f32_e32 v0, 0x4f7ffffe, v0
	v_cvt_u32_f32_e32 v0, v0
	v_mul_lo_u32 v4, v4, v0
	v_mul_hi_u32 v4, v0, v4
	v_add_u32_e32 v0, v0, v4
	v_mul_hi_u32 v0, v3, v0
	v_mul_lo_u32 v4, v0, v2
	v_sub_u32_e32 v4, v3, v4
	v_cmp_ge_u32_e32 vcc, v4, v2
	v_add_u32_e32 v5, 1, v0
	v_add_u32_e32 v3, 1, v3
	v_cndmask_b32_e32 v0, v0, v5, vcc
	v_sub_u32_e32 v5, v4, v2
	v_cndmask_b32_e32 v4, v4, v5, vcc
	v_cmp_ge_u32_e32 vcc, v4, v2
	v_add_u32_e32 v4, 1, v0
	s_nop 0
	v_cndmask_b32_e32 v0, v0, v4, vcc
	v_mul_lo_u32 v4, v2, v0
	v_add_u32_e32 v2, v4, v2
	v_cmp_ne_u32_e32 vcc, v3, v2
	v_mov_b32_e32 v4, v2
	v_mov_b64_e32 v[2:3], s[2:3]
	s_and_saveexec_b64 s[2:3], vcc
	s_cbranch_execz .LBB0_1211
	v_readlane_b32 s4, v252, 11
	v_readlane_b32 s5, v252, 12
	s_mov_b64 s[6:7], 0
	s_nop 3
	global_load_dword v2, v1, s[4:5] sc1
	s_waitcnt vmcnt(0)
	v_cmp_gt_u32_e32 vcc, v4, v2
	s_and_saveexec_b64 s[4:5], vcc
	s_cbranch_execz .LBB0_1210
	s_mov_b32 s16, 1
	s_branch .LBB0_1202

.LBB0_1204:
	v_readlane_b32 s10, v252, 11
	v_readlane_b32 s11, v252, 12
	s_add_i32 s16, s16, 1
	s_mov_b64 s[12:13], -1
	s_nop 2
	global_load_dword v2, v1, s[10:11] sc1
	s_waitcnt vmcnt(0)
	v_cmp_le_u32_e32 vcc, v4, v2
	s_orn2_b64 s[10:11], vcc, exec
	s_branch .LBB0_1201
